# bundle + out-proj residual epilogue: 16 hb loads hoisted (12 up front, 4 re-issued into freed regs), per-step vmcnt(0) drains removed
# speedup vs baseline: 1.0024x; 1.0024x over previous
.LBB0_559:
	v_lshl_add_u32 v152, s16, 8, v142
	v_ashrrev_i32_e32 v153, 31, v152
	v_lshl_or_b32 v150, s6, 8, v143
	v_lshlrev_b64 v[154:155], 12, v[152:153]
	v_ashrrev_i32_e32 v151, 31, v150
	v_lshl_add_u64 v[154:155], s[80:81], 0, v[154:155]
	v_lshl_add_u64 v[154:155], v[150:151], 1, v[154:155]
	global_load_dwordx4 v[188:191], v[154:155], off
	global_load_dwordx4 v[192:195], v[154:155], off offset:256
	v_add_co_u32_e32 v184, vcc, 0x10000, v154
	v_addc_co_u32_e32 v185, vcc, 0, v155, vcc
	global_load_dwordx4 v[196:199], v[184:185], off
	global_load_dwordx4 v[214:217], v[184:185], off offset:256
	v_add_co_u32_e32 v184, vcc, 0x20000, v154
	v_addc_co_u32_e32 v185, vcc, 0, v155, vcc
	global_load_dwordx4 v[218:221], v[184:185], off
	global_load_dwordx4 v[222:225], v[184:185], off offset:256
	v_add_co_u32_e32 v184, vcc, 0x30000, v154
	v_addc_co_u32_e32 v185, vcc, 0, v155, vcc
	global_load_dwordx4 v[226:229], v[184:185], off
	global_load_dwordx4 v[230:233], v[184:185], off offset:256
	v_add_co_u32_e32 v184, vcc, 0x80000, v154
	v_addc_co_u32_e32 v185, vcc, 0, v155, vcc
	global_load_dwordx4 v[234:237], v[184:185], off
	global_load_dwordx4 v[238:241], v[184:185], off offset:256
	v_add_co_u32_e32 v184, vcc, 0x90000, v154
	v_addc_co_u32_e32 v185, vcc, 0, v155, vcc
	global_load_dwordx4 v[242:245], v[184:185], off
	global_load_dwordx4 v[246:249], v[184:185], off offset:256
	s_waitcnt vmcnt(0)
	v_mov_b32_e32 v158, v188
	v_mov_b32_e32 v159, v189
	v_mov_b32_e32 v160, v190
	v_mov_b32_e32 v161, v191
	v_lshlrev_b32_e32 v162, 16, v158
	v_and_b32_e32 v163, 0xffff0000, v158
	v_lshlrev_b32_e32 v158, 16, v159
	v_and_b32_e32 v159, 0xffff0000, v159
	v_pk_add_f32 v[172:173], v[134:135], v[158:159]
	v_pk_add_f32 v[158:159], v[132:133], v[162:163]
	v_lshlrev_b32_e32 v170, 16, v160
	v_and_b32_e32 v171, 0xffff0000, v160
	v_lshlrev_b32_e32 v160, 16, v161
	v_and_b32_e32 v161, 0xffff0000, v161
	v_mul_f32_e32 v157, v159, v159
	v_mul_f32_e32 v167, v173, v173
	v_pk_add_f32 v[162:163], v[130:131], v[160:161]
	v_pk_add_f32 v[160:161], v[128:129], v[170:171]
	v_fmac_f32_e32 v157, v158, v158
	v_fmac_f32_e32 v167, v172, v172
	v_add_f32_e32 v157, v157, v167
	v_mul_f32_e32 v167, v161, v161
	v_fmac_f32_e32 v167, v160, v160
	v_cvt_pk_bf16_f32 v158, v158, v159
	v_cvt_pk_bf16_f32 v159, v172, v173
	v_cvt_pk_bf16_f32 v160, v160, v161
	v_cvt_pk_bf16_f32 v161, v162, v163
	global_store_dwordx4 v[154:155], v[158:161], off
	s_nop 1
	v_mov_b32_e32 v158, v192
	v_mov_b32_e32 v159, v193
	v_mov_b32_e32 v160, v194
	v_mov_b32_e32 v161, v195
	v_add_f32_e32 v157, v167, v157
	v_mul_f32_e32 v167, v163, v163
	v_fmac_f32_e32 v167, v162, v162
	v_add_f32_e32 v157, v167, v157
	v_lshlrev_b32_e32 v162, 16, v158
	v_and_b32_e32 v163, 0xffff0000, v158
	v_lshlrev_b32_e32 v158, 16, v159
	v_and_b32_e32 v159, 0xffff0000, v159
	v_pk_add_f32 v[172:173], v[118:119], v[158:159]
	v_pk_add_f32 v[158:159], v[116:117], v[162:163]
	v_lshlrev_b32_e32 v170, 16, v160
	v_and_b32_e32 v171, 0xffff0000, v160
	v_lshlrev_b32_e32 v160, 16, v161
	v_and_b32_e32 v161, 0xffff0000, v161
	v_mul_f32_e32 v167, v159, v159
	v_mul_f32_e32 v169, v173, v173
	v_pk_add_f32 v[162:163], v[104:105], v[160:161]
	v_pk_add_f32 v[160:161], v[102:103], v[170:171]
	v_fmac_f32_e32 v167, v158, v158
	v_fmac_f32_e32 v169, v172, v172
	v_add_f32_e32 v167, v167, v169
	v_mul_f32_e32 v169, v161, v161
	v_fmac_f32_e32 v169, v160, v160
	v_cvt_pk_bf16_f32 v158, v158, v159
	v_cvt_pk_bf16_f32 v159, v172, v173
	v_cvt_pk_bf16_f32 v160, v160, v161
	v_cvt_pk_bf16_f32 v161, v162, v163
	global_store_dwordx4 v[154:155], v[158:161], off offset:256
	v_and_b32_e32 v155, 64, v210
	v_add_f32_e32 v167, v169, v167
	v_mul_f32_e32 v169, v163, v163
	v_xor_b32_e32 v154, 16, v210
	v_add_u32_e32 v155, 64, v155
	v_fmac_f32_e32 v169, v162, v162
	v_cmp_lt_i32_e32 vcc, v154, v155
	v_add_f32_e32 v167, v169, v167
	v_add_f32_e32 v167, v157, v167
	v_cndmask_b32_e32 v154, v210, v154, vcc
	v_lshlrev_b32_e32 v157, 2, v154
	ds_bpermute_b32 v154, v157, v167
	v_xor_b32_e32 v158, 32, v210
	v_cmp_lt_i32_e32 vcc, v158, v155
	s_waitcnt lgkmcnt(0)
	v_add_f32_e32 v154, v167, v154
	v_cndmask_b32_e32 v155, v210, v158, vcc
	v_lshlrev_b32_e32 v158, 2, v155
	ds_bpermute_b32 v155, v158, v154
	s_and_saveexec_b64 s[8:9], s[38:39]
	s_cbranch_execz .LBB0_561
	s_waitcnt lgkmcnt(0)
	v_add_f32_e32 v159, v154, v155
	s_lshl_b32 s68, s6, 2
	v_lshlrev_b64 v[154:155], 7, v[152:153]
	s_ashr_i32 s69, s68, 31
	v_lshl_add_u64 v[154:155], s[34:35], 0, v[154:155]
	v_lshl_add_u64 v[154:155], s[68:69], 2, v[154:155]
	s_lshl_b32 s88, s61, 2
	v_lshl_add_u64 v[154:155], v[154:155], 0, s[88:89]
	global_store_dword v[154:155], v159, off
.LBB0_561:
	s_or_b64 exec, exec, s[8:9]
	v_or_b32_e32 v154, 16, v152
	s_waitcnt lgkmcnt(0)
	v_ashrrev_i32_e32 v155, 31, v154
	v_lshlrev_b64 v[160:161], 12, v[154:155]
	v_lshl_add_u64 v[160:161], s[80:81], 0, v[160:161]
	v_lshl_add_u64 v[170:171], v[150:151], 1, v[160:161]
	v_mov_b32_e32 v160, v196
	v_mov_b32_e32 v161, v197
	v_mov_b32_e32 v162, v198
	v_mov_b32_e32 v163, v199
	v_lshlrev_b32_e32 v172, 16, v160
	v_and_b32_e32 v173, 0xffff0000, v160
	v_lshlrev_b32_e32 v160, 16, v161
	v_and_b32_e32 v161, 0xffff0000, v161
	v_pk_add_f32 v[186:187], v[126:127], v[160:161]
	v_pk_add_f32 v[160:161], v[124:125], v[172:173]
	v_lshlrev_b32_e32 v184, 16, v162
	v_and_b32_e32 v185, 0xffff0000, v162
	v_lshlrev_b32_e32 v162, 16, v163
	v_and_b32_e32 v163, 0xffff0000, v163
	v_mul_f32_e32 v153, v161, v161
	v_mul_f32_e32 v159, v187, v187
	v_pk_add_f32 v[172:173], v[122:123], v[162:163]
	v_pk_add_f32 v[162:163], v[120:121], v[184:185]
	v_fmac_f32_e32 v153, v160, v160
	v_fmac_f32_e32 v159, v186, v186
	v_add_f32_e32 v153, v153, v159
	v_mul_f32_e32 v159, v163, v163
	v_fmac_f32_e32 v159, v162, v162
	v_cvt_pk_bf16_f32 v160, v160, v161
	v_cvt_pk_bf16_f32 v161, v186, v187
	v_cvt_pk_bf16_f32 v162, v162, v163
	v_cvt_pk_bf16_f32 v163, v172, v173
	global_store_dwordx4 v[170:171], v[160:163], off
	s_nop 1
	v_mov_b32_e32 v160, v214
	v_mov_b32_e32 v161, v215
	v_mov_b32_e32 v162, v216
	v_mov_b32_e32 v163, v217
	v_add_co_u32_e32 v184, vcc, 0x90000, v170
	v_addc_co_u32_e32 v185, vcc, 0, v171, vcc
	global_load_dwordx4 v[188:191], v[184:185], off
	global_load_dwordx4 v[192:195], v[184:185], off offset:256
	v_add_co_u32_e32 v184, vcc, 0xa0000, v170
	v_addc_co_u32_e32 v185, vcc, 0, v171, vcc
	global_load_dwordx4 v[196:199], v[184:185], off
	global_load_dwordx4 v[214:217], v[184:185], off offset:256
	v_add_f32_e32 v153, v159, v153
	v_mul_f32_e32 v159, v173, v173
	v_fmac_f32_e32 v159, v172, v172
	v_add_f32_e32 v153, v159, v153
	v_lshlrev_b32_e32 v172, 16, v160
	v_and_b32_e32 v173, 0xffff0000, v160
	v_lshlrev_b32_e32 v160, 16, v161
	v_and_b32_e32 v161, 0xffff0000, v161
	v_pk_add_f32 v[186:187], v[96:97], v[160:161]
	v_pk_add_f32 v[160:161], v[94:95], v[172:173]
	v_lshlrev_b32_e32 v184, 16, v162
	v_and_b32_e32 v185, 0xffff0000, v162
	v_lshlrev_b32_e32 v162, 16, v163
	v_and_b32_e32 v163, 0xffff0000, v163
	v_mul_f32_e32 v159, v161, v161
	v_mul_f32_e32 v167, v187, v187
	v_pk_add_f32 v[172:173], v[88:89], v[162:163]
	v_pk_add_f32 v[162:163], v[86:87], v[184:185]
	v_fmac_f32_e32 v159, v160, v160
	v_fmac_f32_e32 v167, v186, v186
	v_add_f32_e32 v159, v159, v167
	v_mul_f32_e32 v167, v163, v163
	v_fmac_f32_e32 v167, v162, v162
	v_add_f32_e32 v159, v167, v159
	v_mul_f32_e32 v167, v173, v173
	v_fmac_f32_e32 v167, v172, v172
	v_add_f32_e32 v159, v167, v159
	v_add_f32_e32 v153, v153, v159
	ds_bpermute_b32 v159, v157, v153
	v_cvt_pk_bf16_f32 v160, v160, v161
	v_cvt_pk_bf16_f32 v161, v186, v187
	v_cvt_pk_bf16_f32 v162, v162, v163
	v_cvt_pk_bf16_f32 v163, v172, v173
	s_waitcnt lgkmcnt(0)
	v_add_f32_e32 v153, v153, v159
	ds_bpermute_b32 v159, v158, v153
	global_store_dwordx4 v[170:171], v[160:163], off offset:256
	s_and_saveexec_b64 s[8:9], s[38:39]
	s_cbranch_execz .LBB0_563
	s_lshl_b32 s68, s6, 2
	v_lshlrev_b64 v[154:155], 7, v[154:155]
	s_ashr_i32 s69, s68, 31
	v_lshl_add_u64 v[154:155], s[34:35], 0, v[154:155]
	v_lshl_add_u64 v[154:155], s[68:69], 2, v[154:155]
	s_lshl_b32 s88, s61, 2
	s_waitcnt lgkmcnt(0)
	v_add_f32_e32 v153, v153, v159
	v_lshl_add_u64 v[154:155], v[154:155], 0, s[88:89]
	global_store_dword v[154:155], v153, off
.LBB0_563:
	s_or_b64 exec, exec, s[8:9]
	v_or_b32_e32 v154, 32, v152
	v_ashrrev_i32_e32 v155, 31, v154
	v_lshlrev_b64 v[160:161], 12, v[154:155]
	v_lshl_add_u64 v[160:161], s[80:81], 0, v[160:161]
	v_lshl_add_u64 v[170:171], v[150:151], 1, v[160:161]
	v_mov_b32_e32 v160, v218
	v_mov_b32_e32 v161, v219
	v_mov_b32_e32 v162, v220
	v_mov_b32_e32 v163, v221
	v_lshlrev_b32_e32 v172, 16, v160
	v_and_b32_e32 v173, 0xffff0000, v160
	v_lshlrev_b32_e32 v160, 16, v161
	v_and_b32_e32 v161, 0xffff0000, v161
	v_pk_add_f32 v[186:187], v[108:109], v[160:161]
	v_pk_add_f32 v[160:161], v[106:107], v[172:173]
	v_lshlrev_b32_e32 v184, 16, v162
	v_and_b32_e32 v185, 0xffff0000, v162
	v_lshlrev_b32_e32 v162, 16, v163
	v_and_b32_e32 v163, 0xffff0000, v163
	v_mul_f32_e32 v153, v161, v161
	s_waitcnt lgkmcnt(0)
	v_mul_f32_e32 v159, v187, v187
	v_pk_add_f32 v[172:173], v[100:101], v[162:163]
	v_pk_add_f32 v[162:163], v[98:99], v[184:185]
	v_fmac_f32_e32 v153, v160, v160
	v_fmac_f32_e32 v159, v186, v186
	v_add_f32_e32 v153, v153, v159
	v_mul_f32_e32 v159, v163, v163
	v_fmac_f32_e32 v159, v162, v162
	v_cvt_pk_bf16_f32 v160, v160, v161
	v_cvt_pk_bf16_f32 v161, v186, v187
	v_cvt_pk_bf16_f32 v162, v162, v163
	v_cvt_pk_bf16_f32 v163, v172, v173
	global_store_dwordx4 v[170:171], v[160:163], off
	s_nop 1
	v_mov_b32_e32 v160, v222
	v_mov_b32_e32 v161, v223
	v_mov_b32_e32 v162, v224
	v_mov_b32_e32 v163, v225
	v_add_f32_e32 v153, v159, v153
	v_mul_f32_e32 v159, v173, v173
	v_fmac_f32_e32 v159, v172, v172
	v_add_f32_e32 v153, v159, v153
	v_lshlrev_b32_e32 v172, 16, v160
	v_and_b32_e32 v173, 0xffff0000, v160
	v_lshlrev_b32_e32 v160, 16, v161
	v_and_b32_e32 v161, 0xffff0000, v161
	v_pk_add_f32 v[186:187], v[80:81], v[160:161]
	v_pk_add_f32 v[160:161], v[78:79], v[172:173]
	v_lshlrev_b32_e32 v184, 16, v162
	v_and_b32_e32 v185, 0xffff0000, v162
	v_lshlrev_b32_e32 v162, 16, v163
	v_and_b32_e32 v163, 0xffff0000, v163
	v_mul_f32_e32 v159, v161, v161
	v_mul_f32_e32 v167, v187, v187
	v_pk_add_f32 v[172:173], v[76:77], v[162:163]
	v_pk_add_f32 v[162:163], v[74:75], v[184:185]
	v_fmac_f32_e32 v159, v160, v160
	v_fmac_f32_e32 v167, v186, v186
	v_add_f32_e32 v159, v159, v167
	v_mul_f32_e32 v167, v163, v163
	v_fmac_f32_e32 v167, v162, v162
	v_add_f32_e32 v159, v167, v159
	v_mul_f32_e32 v167, v173, v173
	v_fmac_f32_e32 v167, v172, v172
	v_add_f32_e32 v159, v167, v159
	v_add_f32_e32 v153, v153, v159
	ds_bpermute_b32 v159, v157, v153
	v_cvt_pk_bf16_f32 v160, v160, v161
	v_cvt_pk_bf16_f32 v161, v186, v187
	v_cvt_pk_bf16_f32 v162, v162, v163
	v_cvt_pk_bf16_f32 v163, v172, v173
	s_waitcnt lgkmcnt(0)
	v_add_f32_e32 v153, v153, v159
	ds_bpermute_b32 v159, v158, v153
	global_store_dwordx4 v[170:171], v[160:163], off offset:256
	s_and_saveexec_b64 s[8:9], s[38:39]
	s_cbranch_execz .LBB0_565
	s_lshl_b32 s68, s6, 2
	v_lshlrev_b64 v[154:155], 7, v[154:155]
	s_ashr_i32 s69, s68, 31
	v_lshl_add_u64 v[154:155], s[34:35], 0, v[154:155]
	v_lshl_add_u64 v[154:155], s[68:69], 2, v[154:155]
	s_lshl_b32 s88, s61, 2
	s_waitcnt lgkmcnt(0)
	v_add_f32_e32 v153, v153, v159
	v_lshl_add_u64 v[154:155], v[154:155], 0, s[88:89]
	global_store_dword v[154:155], v153, off
.LBB0_565:
	s_or_b64 exec, exec, s[8:9]
	v_or_b32_e32 v154, 48, v152
	v_ashrrev_i32_e32 v155, 31, v154
	v_lshlrev_b64 v[160:161], 12, v[154:155]
	v_lshl_add_u64 v[160:161], s[80:81], 0, v[160:161]
	v_lshl_add_u64 v[170:171], v[150:151], 1, v[160:161]
	v_mov_b32_e32 v160, v226
	v_mov_b32_e32 v161, v227
	v_mov_b32_e32 v162, v228
	v_mov_b32_e32 v163, v229
	v_lshlrev_b32_e32 v172, 16, v160
	v_and_b32_e32 v173, 0xffff0000, v160
	v_lshlrev_b32_e32 v160, 16, v161
	v_and_b32_e32 v161, 0xffff0000, v161
	v_pk_add_f32 v[186:187], v[92:93], v[160:161]
	v_pk_add_f32 v[160:161], v[90:91], v[172:173]
	v_lshlrev_b32_e32 v184, 16, v162
	v_and_b32_e32 v185, 0xffff0000, v162
	v_lshlrev_b32_e32 v162, 16, v163
	v_and_b32_e32 v163, 0xffff0000, v163
	v_mul_f32_e32 v153, v161, v161
	s_waitcnt lgkmcnt(0)
	v_mul_f32_e32 v159, v187, v187
	v_pk_add_f32 v[172:173], v[84:85], v[162:163]
	v_pk_add_f32 v[162:163], v[82:83], v[184:185]
	v_fmac_f32_e32 v153, v160, v160
	v_fmac_f32_e32 v159, v186, v186
	v_add_f32_e32 v153, v153, v159
	v_mul_f32_e32 v159, v163, v163
	v_fmac_f32_e32 v159, v162, v162
	v_cvt_pk_bf16_f32 v160, v160, v161
	v_cvt_pk_bf16_f32 v161, v186, v187
	v_cvt_pk_bf16_f32 v162, v162, v163
	v_cvt_pk_bf16_f32 v163, v172, v173
	global_store_dwordx4 v[170:171], v[160:163], off
	s_nop 1
	v_mov_b32_e32 v160, v230
	v_mov_b32_e32 v161, v231
	v_mov_b32_e32 v162, v232
	v_mov_b32_e32 v163, v233
	v_add_f32_e32 v153, v159, v153
	v_mul_f32_e32 v159, v173, v173
	v_fmac_f32_e32 v159, v172, v172
	v_add_f32_e32 v153, v159, v153
	v_lshlrev_b32_e32 v172, 16, v160
	v_and_b32_e32 v173, 0xffff0000, v160
	v_lshlrev_b32_e32 v160, 16, v161
	v_and_b32_e32 v161, 0xffff0000, v161
	v_pk_add_f32 v[186:187], v[72:73], v[160:161]
	v_pk_add_f32 v[160:161], v[70:71], v[172:173]
	v_lshlrev_b32_e32 v184, 16, v162
	v_and_b32_e32 v185, 0xffff0000, v162
	v_lshlrev_b32_e32 v162, 16, v163
	v_and_b32_e32 v163, 0xffff0000, v163
	v_mul_f32_e32 v159, v161, v161
	v_mul_f32_e32 v167, v187, v187
	v_pk_add_f32 v[172:173], v[68:69], v[162:163]
	v_pk_add_f32 v[162:163], v[66:67], v[184:185]
	v_fmac_f32_e32 v159, v160, v160
	v_fmac_f32_e32 v167, v186, v186
	v_add_f32_e32 v159, v159, v167
	v_mul_f32_e32 v167, v163, v163
	v_fmac_f32_e32 v167, v162, v162
	v_add_f32_e32 v159, v167, v159
	v_mul_f32_e32 v167, v173, v173
	v_fmac_f32_e32 v167, v172, v172
	v_add_f32_e32 v159, v167, v159
	v_add_f32_e32 v153, v153, v159
	ds_bpermute_b32 v159, v157, v153
	v_cvt_pk_bf16_f32 v160, v160, v161
	v_cvt_pk_bf16_f32 v161, v186, v187
	v_cvt_pk_bf16_f32 v162, v162, v163
	v_cvt_pk_bf16_f32 v163, v172, v173
	s_waitcnt lgkmcnt(0)
	v_add_f32_e32 v153, v153, v159
	ds_bpermute_b32 v159, v158, v153
	global_store_dwordx4 v[170:171], v[160:163], off offset:256
	s_and_saveexec_b64 s[8:9], s[38:39]
	s_cbranch_execz .LBB0_567
	s_lshl_b32 s68, s6, 2
	v_lshlrev_b64 v[154:155], 7, v[154:155]
	s_ashr_i32 s69, s68, 31
	v_lshl_add_u64 v[154:155], s[34:35], 0, v[154:155]
	v_lshl_add_u64 v[154:155], s[68:69], 2, v[154:155]
	s_lshl_b32 s88, s61, 2
	s_waitcnt lgkmcnt(0)
	v_add_f32_e32 v153, v153, v159
	v_lshl_add_u64 v[154:155], v[154:155], 0, s[88:89]
	global_store_dword v[154:155], v153, off
.LBB0_567:
	s_or_b64 exec, exec, s[8:9]
	v_add_u32_e32 v154, 0x80, v152
	v_ashrrev_i32_e32 v155, 31, v154
	v_lshlrev_b64 v[160:161], 12, v[154:155]
	v_lshl_add_u64 v[160:161], s[80:81], 0, v[160:161]
	v_lshl_add_u64 v[170:171], v[150:151], 1, v[160:161]
	v_mov_b32_e32 v160, v234
	v_mov_b32_e32 v161, v235
	v_mov_b32_e32 v162, v236
	v_mov_b32_e32 v163, v237
	v_lshlrev_b32_e32 v172, 16, v160
	v_and_b32_e32 v173, 0xffff0000, v160
	v_lshlrev_b32_e32 v160, 16, v161
	v_and_b32_e32 v161, 0xffff0000, v161
	v_pk_add_f32 v[186:187], v[64:65], v[160:161]
	v_pk_add_f32 v[160:161], v[62:63], v[172:173]
	v_lshlrev_b32_e32 v184, 16, v162
	v_and_b32_e32 v185, 0xffff0000, v162
	v_lshlrev_b32_e32 v162, 16, v163
	v_and_b32_e32 v163, 0xffff0000, v163
	v_mul_f32_e32 v153, v161, v161
	s_waitcnt lgkmcnt(0)
	v_mul_f32_e32 v159, v187, v187
	v_pk_add_f32 v[172:173], v[60:61], v[162:163]
	v_pk_add_f32 v[162:163], v[58:59], v[184:185]
	v_fmac_f32_e32 v153, v160, v160
	v_fmac_f32_e32 v159, v186, v186
	v_add_f32_e32 v153, v153, v159
	v_mul_f32_e32 v159, v163, v163
	v_fmac_f32_e32 v159, v162, v162
	v_cvt_pk_bf16_f32 v160, v160, v161
	v_cvt_pk_bf16_f32 v161, v186, v187
	v_cvt_pk_bf16_f32 v162, v162, v163
	v_cvt_pk_bf16_f32 v163, v172, v173
	global_store_dwordx4 v[170:171], v[160:163], off
	s_nop 1
	v_mov_b32_e32 v160, v238
	v_mov_b32_e32 v161, v239
	v_mov_b32_e32 v162, v240
	v_mov_b32_e32 v163, v241
	v_add_f32_e32 v153, v159, v153
	v_mul_f32_e32 v159, v173, v173
	v_fmac_f32_e32 v159, v172, v172
	v_add_f32_e32 v153, v159, v153
	v_lshlrev_b32_e32 v172, 16, v160
	v_and_b32_e32 v173, 0xffff0000, v160
	v_lshlrev_b32_e32 v160, 16, v161
	v_and_b32_e32 v161, 0xffff0000, v161
	v_pk_add_f32 v[186:187], v[48:49], v[160:161]
	v_pk_add_f32 v[160:161], v[46:47], v[172:173]
	v_lshlrev_b32_e32 v184, 16, v162
	v_and_b32_e32 v185, 0xffff0000, v162
	v_lshlrev_b32_e32 v162, 16, v163
	v_and_b32_e32 v163, 0xffff0000, v163
	v_mul_f32_e32 v159, v161, v161
	v_mul_f32_e32 v167, v187, v187
	v_pk_add_f32 v[172:173], v[40:41], v[162:163]
	v_pk_add_f32 v[162:163], v[38:39], v[184:185]
	v_fmac_f32_e32 v159, v160, v160
	v_fmac_f32_e32 v167, v186, v186
	v_add_f32_e32 v159, v159, v167
	v_mul_f32_e32 v167, v163, v163
	v_fmac_f32_e32 v167, v162, v162
	v_add_f32_e32 v159, v167, v159
	v_mul_f32_e32 v167, v173, v173
	v_fmac_f32_e32 v167, v172, v172
	v_add_f32_e32 v159, v167, v159
	v_add_f32_e32 v153, v153, v159
	ds_bpermute_b32 v159, v157, v153
	v_cvt_pk_bf16_f32 v160, v160, v161
	v_cvt_pk_bf16_f32 v161, v186, v187
	v_cvt_pk_bf16_f32 v162, v162, v163
	v_cvt_pk_bf16_f32 v163, v172, v173
	s_waitcnt lgkmcnt(0)
	v_add_f32_e32 v153, v153, v159
	ds_bpermute_b32 v159, v158, v153
	global_store_dwordx4 v[170:171], v[160:163], off offset:256
	s_and_saveexec_b64 s[8:9], s[38:39]
	s_cbranch_execz .LBB0_569
	s_lshl_b32 s68, s6, 2
	v_lshlrev_b64 v[154:155], 7, v[154:155]
	s_ashr_i32 s69, s68, 31
	v_lshl_add_u64 v[154:155], s[34:35], 0, v[154:155]
	v_lshl_add_u64 v[154:155], s[68:69], 2, v[154:155]
	s_lshl_b32 s88, s61, 2
	s_waitcnt lgkmcnt(0)
	v_add_f32_e32 v153, v153, v159
	v_lshl_add_u64 v[154:155], v[154:155], 0, s[88:89]
	global_store_dword v[154:155], v153, off
.LBB0_569:
	s_or_b64 exec, exec, s[8:9]
	v_add_u32_e32 v154, 0x90, v152
	v_ashrrev_i32_e32 v155, 31, v154
	v_lshlrev_b64 v[160:161], 12, v[154:155]
	v_lshl_add_u64 v[160:161], s[80:81], 0, v[160:161]
	v_lshl_add_u64 v[170:171], v[150:151], 1, v[160:161]
	v_mov_b32_e32 v160, v242
	v_mov_b32_e32 v161, v243
	v_mov_b32_e32 v162, v244
	v_mov_b32_e32 v163, v245
	v_lshlrev_b32_e32 v172, 16, v160
	v_and_b32_e32 v173, 0xffff0000, v160
	v_lshlrev_b32_e32 v160, 16, v161
	v_and_b32_e32 v161, 0xffff0000, v161
	v_pk_add_f32 v[186:187], v[56:57], v[160:161]
	v_pk_add_f32 v[160:161], v[54:55], v[172:173]
	v_lshlrev_b32_e32 v184, 16, v162
	v_and_b32_e32 v185, 0xffff0000, v162
	v_lshlrev_b32_e32 v162, 16, v163
	v_and_b32_e32 v163, 0xffff0000, v163
	v_mul_f32_e32 v153, v161, v161
	s_waitcnt lgkmcnt(0)
	v_mul_f32_e32 v159, v187, v187
	v_pk_add_f32 v[172:173], v[52:53], v[162:163]
	v_pk_add_f32 v[162:163], v[50:51], v[184:185]
	v_fmac_f32_e32 v153, v160, v160
	v_fmac_f32_e32 v159, v186, v186
	v_add_f32_e32 v153, v153, v159
	v_mul_f32_e32 v159, v163, v163
	v_fmac_f32_e32 v159, v162, v162
	v_cvt_pk_bf16_f32 v160, v160, v161
	v_cvt_pk_bf16_f32 v161, v186, v187
	v_cvt_pk_bf16_f32 v162, v162, v163
	v_cvt_pk_bf16_f32 v163, v172, v173
	global_store_dwordx4 v[170:171], v[160:163], off
	s_nop 1
	v_mov_b32_e32 v160, v246
	v_mov_b32_e32 v161, v247
	v_mov_b32_e32 v162, v248
	v_mov_b32_e32 v163, v249
	v_add_f32_e32 v153, v159, v153
	v_mul_f32_e32 v159, v173, v173
	v_fmac_f32_e32 v159, v172, v172
	v_add_f32_e32 v153, v159, v153
	v_lshlrev_b32_e32 v172, 16, v160
	v_and_b32_e32 v173, 0xffff0000, v160
	v_lshlrev_b32_e32 v160, 16, v161
	v_and_b32_e32 v161, 0xffff0000, v161
	v_pk_add_f32 v[186:187], v[32:33], v[160:161]
	v_pk_add_f32 v[160:161], v[30:31], v[172:173]
	v_lshlrev_b32_e32 v184, 16, v162
	v_and_b32_e32 v185, 0xffff0000, v162
	v_lshlrev_b32_e32 v162, 16, v163
	v_and_b32_e32 v163, 0xffff0000, v163
	v_mul_f32_e32 v159, v161, v161
	v_mul_f32_e32 v167, v187, v187
	v_pk_add_f32 v[172:173], v[24:25], v[162:163]
	v_pk_add_f32 v[162:163], v[22:23], v[184:185]
	v_fmac_f32_e32 v159, v160, v160
	v_fmac_f32_e32 v167, v186, v186
	v_add_f32_e32 v159, v159, v167
	v_mul_f32_e32 v167, v163, v163
	v_fmac_f32_e32 v167, v162, v162
	v_add_f32_e32 v159, v167, v159
	v_mul_f32_e32 v167, v173, v173
	v_fmac_f32_e32 v167, v172, v172
	v_add_f32_e32 v159, v167, v159
	v_add_f32_e32 v153, v153, v159
	ds_bpermute_b32 v159, v157, v153
	v_cvt_pk_bf16_f32 v160, v160, v161
	v_cvt_pk_bf16_f32 v161, v186, v187
	v_cvt_pk_bf16_f32 v162, v162, v163
	v_cvt_pk_bf16_f32 v163, v172, v173
	s_waitcnt lgkmcnt(0)
	v_add_f32_e32 v153, v153, v159
	ds_bpermute_b32 v159, v158, v153
	global_store_dwordx4 v[170:171], v[160:163], off offset:256
	s_and_saveexec_b64 s[8:9], s[38:39]
	s_cbranch_execz .LBB0_571
	s_lshl_b32 s68, s6, 2
	v_lshlrev_b64 v[154:155], 7, v[154:155]
	s_ashr_i32 s69, s68, 31
	v_lshl_add_u64 v[154:155], s[34:35], 0, v[154:155]
	v_lshl_add_u64 v[154:155], s[68:69], 2, v[154:155]
	s_lshl_b32 s88, s61, 2
	s_waitcnt lgkmcnt(0)
	v_add_f32_e32 v153, v153, v159
	v_lshl_add_u64 v[154:155], v[154:155], 0, s[88:89]
	global_store_dword v[154:155], v153, off
.LBB0_571:
	s_or_b64 exec, exec, s[8:9]
	v_add_u32_e32 v154, 0xa0, v152
	v_ashrrev_i32_e32 v155, 31, v154
	v_lshlrev_b64 v[160:161], 12, v[154:155]
	v_lshl_add_u64 v[160:161], s[80:81], 0, v[160:161]
	v_lshl_add_u64 v[170:171], v[150:151], 1, v[160:161]
	s_waitcnt vmcnt(6)
	v_mov_b32_e32 v160, v188
	v_mov_b32_e32 v161, v189
	v_mov_b32_e32 v162, v190
	v_mov_b32_e32 v163, v191
	v_lshlrev_b32_e32 v172, 16, v160
	v_and_b32_e32 v173, 0xffff0000, v160
	v_lshlrev_b32_e32 v160, 16, v161
	v_and_b32_e32 v161, 0xffff0000, v161
	v_pk_add_f32 v[186:187], v[44:45], v[160:161]
	v_pk_add_f32 v[160:161], v[42:43], v[172:173]
	v_lshlrev_b32_e32 v184, 16, v162
	v_and_b32_e32 v185, 0xffff0000, v162
	v_lshlrev_b32_e32 v162, 16, v163
	v_and_b32_e32 v163, 0xffff0000, v163
	v_mul_f32_e32 v153, v161, v161
	s_waitcnt lgkmcnt(0)
	v_mul_f32_e32 v159, v187, v187
	v_pk_add_f32 v[172:173], v[36:37], v[162:163]
	v_pk_add_f32 v[162:163], v[34:35], v[184:185]
	v_fmac_f32_e32 v153, v160, v160
	v_fmac_f32_e32 v159, v186, v186
	v_add_f32_e32 v153, v153, v159
	v_mul_f32_e32 v159, v163, v163
	v_fmac_f32_e32 v159, v162, v162
	v_cvt_pk_bf16_f32 v160, v160, v161
	v_cvt_pk_bf16_f32 v161, v186, v187
	v_cvt_pk_bf16_f32 v162, v162, v163
	v_cvt_pk_bf16_f32 v163, v172, v173
	global_store_dwordx4 v[170:171], v[160:163], off
	s_nop 1
	v_mov_b32_e32 v160, v192
	v_mov_b32_e32 v161, v193
	v_mov_b32_e32 v162, v194
	v_mov_b32_e32 v163, v195
	v_add_f32_e32 v153, v159, v153
	v_mul_f32_e32 v159, v173, v173
	v_fmac_f32_e32 v159, v172, v172
	v_add_f32_e32 v153, v159, v153
	v_lshlrev_b32_e32 v172, 16, v160
	v_and_b32_e32 v173, 0xffff0000, v160
	v_lshlrev_b32_e32 v160, 16, v161
	v_and_b32_e32 v161, 0xffff0000, v161
	v_pk_add_f32 v[186:187], v[16:17], v[160:161]
	v_pk_add_f32 v[160:161], v[14:15], v[172:173]
	v_lshlrev_b32_e32 v184, 16, v162
	v_and_b32_e32 v185, 0xffff0000, v162
	v_lshlrev_b32_e32 v162, 16, v163
	v_and_b32_e32 v163, 0xffff0000, v163
	v_mul_f32_e32 v159, v161, v161
	v_mul_f32_e32 v167, v187, v187
	v_pk_add_f32 v[172:173], v[12:13], v[162:163]
	v_pk_add_f32 v[162:163], v[10:11], v[184:185]
	v_fmac_f32_e32 v159, v160, v160
	v_fmac_f32_e32 v167, v186, v186
	v_add_f32_e32 v159, v159, v167
	v_mul_f32_e32 v167, v163, v163
	v_fmac_f32_e32 v167, v162, v162
	v_add_f32_e32 v159, v167, v159
	v_mul_f32_e32 v167, v173, v173
	v_fmac_f32_e32 v167, v172, v172
	v_add_f32_e32 v159, v167, v159
	v_add_f32_e32 v153, v153, v159
	ds_bpermute_b32 v159, v157, v153
	v_cvt_pk_bf16_f32 v160, v160, v161
	v_cvt_pk_bf16_f32 v161, v186, v187
	v_cvt_pk_bf16_f32 v162, v162, v163
	v_cvt_pk_bf16_f32 v163, v172, v173
	s_waitcnt lgkmcnt(0)
	v_add_f32_e32 v153, v153, v159
	ds_bpermute_b32 v159, v158, v153
	global_store_dwordx4 v[170:171], v[160:163], off offset:256
	s_and_saveexec_b64 s[8:9], s[38:39]
	s_cbranch_execz .LBB0_573
	s_lshl_b32 s68, s6, 2
	v_lshlrev_b64 v[154:155], 7, v[154:155]
	s_ashr_i32 s69, s68, 31
	v_lshl_add_u64 v[154:155], s[34:35], 0, v[154:155]
	v_lshl_add_u64 v[154:155], s[68:69], 2, v[154:155]
	s_lshl_b32 s88, s61, 2
	s_waitcnt lgkmcnt(0)
	v_add_f32_e32 v153, v153, v159
	v_lshl_add_u64 v[154:155], v[154:155], 0, s[88:89]
	global_store_dword v[154:155], v153, off
.LBB0_573:
	s_or_b64 exec, exec, s[8:9]
	v_add_u32_e32 v152, 0xb0, v152
	v_ashrrev_i32_e32 v153, 31, v152
	v_lshlrev_b64 v[154:155], 12, v[152:153]
	v_lshl_add_u64 v[154:155], s[80:81], 0, v[154:155]
	v_lshl_add_u64 v[150:151], v[150:151], 1, v[154:155]
	v_mov_b32_e32 v160, v196
	v_mov_b32_e32 v161, v197
	v_mov_b32_e32 v162, v198
	v_mov_b32_e32 v163, v199
	v_lshlrev_b32_e32 v154, 16, v160
	v_and_b32_e32 v155, 0xffff0000, v160
	v_lshlrev_b32_e32 v160, 16, v161
	v_and_b32_e32 v161, 0xffff0000, v161
	v_pk_add_f32 v[172:173], v[28:29], v[160:161]
	v_pk_add_f32 v[154:155], v[26:27], v[154:155]
	v_lshlrev_b32_e32 v170, 16, v162
	v_and_b32_e32 v171, 0xffff0000, v162
	v_lshlrev_b32_e32 v162, 16, v163
	v_and_b32_e32 v163, 0xffff0000, v163
	s_waitcnt lgkmcnt(0)
	v_mul_f32_e32 v159, v155, v155
	v_mul_f32_e32 v160, v173, v173
	v_pk_add_f32 v[184:185], v[20:21], v[162:163]
	v_pk_add_f32 v[162:163], v[18:19], v[170:171]
	v_fmac_f32_e32 v159, v154, v154
	v_fmac_f32_e32 v160, v172, v172
	v_add_f32_e32 v159, v159, v160
	v_mul_f32_e32 v160, v163, v163
	v_fmac_f32_e32 v160, v162, v162
	v_add_f32_e32 v159, v160, v159
	v_mul_f32_e32 v160, v185, v185
	v_fmac_f32_e32 v160, v184, v184
	v_add_f32_e32 v159, v160, v159
	v_cvt_pk_bf16_f32 v160, v154, v155
	v_cvt_pk_bf16_f32 v161, v172, v173
	v_cvt_pk_bf16_f32 v162, v162, v163
	v_cvt_pk_bf16_f32 v163, v184, v185
	global_store_dwordx4 v[150:151], v[160:163], off
	s_nop 1
	v_mov_b32_e32 v160, v214
	v_mov_b32_e32 v161, v215
	v_mov_b32_e32 v162, v216
	v_mov_b32_e32 v163, v217
	v_lshlrev_b32_e32 v154, 16, v160
	v_and_b32_e32 v155, 0xffff0000, v160
	v_lshlrev_b32_e32 v160, 16, v161
	v_and_b32_e32 v161, 0xffff0000, v161
	v_pk_add_f32 v[172:173], v[8:9], v[160:161]
	v_pk_add_f32 v[154:155], v[6:7], v[154:155]
	v_lshlrev_b32_e32 v170, 16, v162
	v_and_b32_e32 v171, 0xffff0000, v162
	v_lshlrev_b32_e32 v162, 16, v163
	v_and_b32_e32 v163, 0xffff0000, v163
	v_mul_f32_e32 v160, v155, v155
	v_mul_f32_e32 v161, v173, v173
	v_pk_add_f32 v[184:185], v[4:5], v[162:163]
	v_pk_add_f32 v[162:163], v[2:3], v[170:171]
	v_fmac_f32_e32 v160, v154, v154
	v_fmac_f32_e32 v161, v172, v172
	v_add_f32_e32 v160, v160, v161
	v_mul_f32_e32 v161, v163, v163
	v_fmac_f32_e32 v161, v162, v162
	v_add_f32_e32 v160, v161, v160
	v_mul_f32_e32 v161, v185, v185
	v_fmac_f32_e32 v161, v184, v184
	v_add_f32_e32 v160, v161, v160
	v_add_f32_e32 v159, v159, v160
	v_cvt_pk_bf16_f32 v160, v154, v155
	v_cvt_pk_bf16_f32 v161, v172, v173
	v_cvt_pk_bf16_f32 v162, v162, v163
	v_cvt_pk_bf16_f32 v163, v184, v185
	global_store_dwordx4 v[150:151], v[160:163], off offset:256
	ds_bpermute_b32 v150, v157, v159
	s_waitcnt lgkmcnt(0)
	v_add_f32_e32 v150, v159, v150
	ds_bpermute_b32 v151, v158, v150
	s_and_saveexec_b64 s[8:9], s[38:39]
	s_cbranch_execz .LBB0_575
	s_waitcnt lgkmcnt(0)
	v_add_f32_e32 v154, v150, v151
	s_lshl_b32 s68, s6, 2
	v_lshlrev_b64 v[150:151], 7, v[152:153]
	s_ashr_i32 s69, s68, 31
	v_lshl_add_u64 v[150:151], s[34:35], 0, v[150:151]
	v_lshl_add_u64 v[150:151], s[68:69], 2, v[150:151]
	s_lshl_b32 s88, s61, 2
	v_lshl_add_u64 v[150:151], v[150:151], 0, s[88:89]
	global_store_dword v[150:151], v154, off
